# P4 work queue: next-unit atomic made non-blocking (return consumed at unit end instead of vmcnt(0) right after issue), on top of v45
# speedup vs baseline: 1.0006x; 1.0006x over previous
.LBB0_870:
	s_mov_b64 s[98:99], exec
	v_readlane_b32 s100, v240, 3
	v_readlane_b32 s101, v240, 4
	s_and_b64 s[100:101], s[98:99], s[100:101]
	s_mov_b64 exec, s[100:101]
	s_cbranch_execz .Lq_skip
	s_waitcnt vmcnt(0)
	v_readfirstlane_b32 s100, v251
	s_nop 1
	v_add_u32_e32 v139, s100, v250
.Lq_skip:
	s_mov_b64 exec, s[98:99]
	v_lshl_add_u64 v[30:31], s[96:97], 1, v[30:31]
	v_and_b32_e32 v35, 32, v211
	v_lshrrev_b32_e32 v35, 2, v35
	v_lshl_add_u32 v34, v138, 1, v35
	v_mov_b32_e32 v35, v151
	v_lshl_add_u64 v[30:31], v[30:31], 0, v[34:35]
	v_cvt_pk_bf16_f32 v36, v32, v33
	v_cvt_pk_bf16_f32 v37, v16, v17
	v_cvt_pk_bf16_f32 v38, v18, v19
	v_cvt_pk_bf16_f32 v39, v20, v21
	v_cvt_pk_bf16_f32 v40, v22, v23
	v_cvt_pk_bf16_f32 v41, v24, v25
	v_cvt_pk_bf16_f32 v42, v26, v27
	v_cvt_pk_bf16_f32 v43, v28, v29
	v_readlane_b32 s2, v240, 24
	v_permlane32_swap_b32_e32 v36, v38
	v_permlane32_swap_b32_e32 v37, v39
	v_cvt_pk_bf16_f32 v44, v0, v1
	v_cvt_pk_bf16_f32 v45, v2, v3
	global_store_dwordx4 v[30:31], v[36:39], off
	v_cvt_pk_bf16_f32 v46, v4, v5
	v_cvt_pk_bf16_f32 v47, v6, v7
	v_readlane_b32 s3, v240, 25
	v_permlane32_swap_b32_e32 v40, v42
	v_permlane32_swap_b32_e32 v41, v43
	v_cvt_pk_bf16_f32 v48, v8, v9
	v_cvt_pk_bf16_f32 v49, v10, v11
	global_store_dwordx4 v[30:31], v[40:43], off offset:32
	v_cvt_pk_bf16_f32 v50, v12, v13
	v_cvt_pk_bf16_f32 v51, v14, v15
	v_readlane_b32 s14, v240, 15
	v_readlane_b32 s55, v240, 20
	v_permlane32_swap_b32_e32 v44, v46
	v_permlane32_swap_b32_e32 v45, v47
	global_store_dwordx4 v[30:31], v[44:47], off offset:64
	s_nop 1
	v_permlane32_swap_b32_e32 v48, v50
	v_permlane32_swap_b32_e32 v49, v51
	global_store_dwordx4 v[30:31], v[48:51], off offset:96

.LBB0_880:
	v_writelane_b32 v240, s2, 24
	s_nop 1
	v_writelane_b32 v240, s3, 25
	s_mov_b64 s[4:5], exec
	v_readlane_b32 s2, v240, 3
	v_readlane_b32 s3, v240, 4
	s_and_b64 s[2:3], s[4:5], s[2:3]
	s_mov_b64 exec, s[2:3]
	s_cbranch_execz .LBB0_884
	s_mov_b64 s[16:17], exec
	v_mbcnt_lo_u32_b32 v0, s16, 0
	v_mbcnt_hi_u32_b32 v0, s17, v0
	v_cmp_eq_u32_e32 vcc, 0, v0
	s_and_saveexec_b64 s[14:15], vcc
	s_cbranch_execz .LBB0_883
	s_bcnt1_i32_b64 s1, s[16:17]
	v_mov_b32_e32 v251, s1
	global_atomic_add v251, v151, v251, s[86:87] sc0
.LBB0_883:
	s_or_b64 exec, exec, s[14:15]
	v_mov_b32_e32 v250, v0
